# stack + next-unit residual tile L2 touch prefetch in GEMM3/GEMM5 epilogues
# baseline (speedup 1.0000x reference)
;     __device__ __forceinline__ void operator()(const f32x4 (&acc)[2][2][4][2], const Unit& u, int wr, int wc, int fr, int fq) const {
;     ...
;             if (basef) {
; #pragma unroll
;                 for (int m = 0; m < 4; ++m) { const size_t off = (size_t)(row0 + ai * HALF + m * 16) * ldc + col0;
; #pragma unroll
;                     for (int bj = 0; bj < 2; ++bj) { bs[m][bj][0] = *(const f32x4*)(basef + off + bj * HALF); bs[m][bj][1] = *(const f32x4*)(basef + off + bj * HALF + 4); } }
;             } else {
;                 u32x4 rb[4][2];
; #pragma unroll
;                 for (int m = 0; m < 4; ++m) { const size_t off = (size_t)(row0 + ai * HALF + m * 16) * ldc + col0;
; #pragma unroll
;                     for (int bj = 0; bj < 2; ++bj) rb[m][bj] = *(const u32x4*)(baseb + off + bj * HALF); }
.LBB0_67:
	v_lshrrev_b32_e32 v232, 1, v242
	v_and_b32_e32 v231, 1, v242
	v_lshl_add_u32 v232, s60, 8, v232
	v_mov_b32_e32 v233, 0
	s_and_b64 vcc, exec, s[54:55]
	s_cbranch_vccz .Lrp3_bf16
	v_lshlrev_b32_e32 v231, 9, v231
	v_lshlrev_b32_e32 v232, 12, v232
	v_lshl_add_u32 v231, s18, 10, v231
	v_add_u32_e32 v232, v232, v231
	v_lshl_add_u64 v[232:233], v[232:233], 0, s[52:53]
	global_load_dword v243, v[232:233], off
	global_load_dword v243, v[232:233], off offset:128
	global_load_dword v243, v[232:233], off offset:256
	global_load_dword v243, v[232:233], off offset:384
	s_branch .Lrp3_done
.Lrp3_bf16:
	v_lshlrev_b32_e32 v231, 8, v231
	v_lshlrev_b32_e32 v232, 11, v232
	v_lshl_add_u32 v231, s18, 9, v231
	v_add_u32_e32 v232, v232, v231
	v_lshl_add_u64 v[232:233], v[232:233], 0, s[6:7]
	global_load_dword v243, v[232:233], off
	global_load_dword v243, v[232:233], off offset:128

;     __device__ __forceinline__ void operator()(const f32x4 (&acc)[2][2][4][2], const Unit& u, int wr, int wc, int fr, int fq) const {
;     ...
;                 u32x4 rb[4][2];
; #pragma unroll
;                 for (int m = 0; m < 4; ++m) { const size_t off = (size_t)(row0 + ai * HALF + m * 16) * ldc + col0;
; #pragma unroll
;                     for (int bj = 0; bj < 2; ++bj) rb[m][bj] = *(const u32x4*)(baseb + off + bj * HALF); }
.LBB0_175:
	v_lshrrev_b32_e32 v246, 1, v242
	v_and_b32_e32 v248, 1, v242
	v_lshl_add_u32 v246, s22, 8, v246
	v_lshlrev_b32_e32 v248, 8, v248
	v_lshlrev_b32_e32 v246, 11, v246
	v_lshl_add_u32 v248, s62, 9, v248
	v_mov_b32_e32 v247, 0
	v_add_u32_e32 v246, v246, v248
	v_lshl_add_u64 v[246:247], v[246:247], 0, s[14:15]
	global_load_dword v249, v[246:247], off
	global_load_dword v250, v[246:247], off offset:128
	v_lshl_add_u32 v174, s63, 8, v3
	v_lshl_or_b32 v170, s64, 8, v187
	v_ashrrev_i32_e32 v171, 31, v170
	v_ashrrev_i32_e32 v175, 31, v174
	v_lshl_add_u64 v[172:173], v[170:171], 1, s[14:15]
	v_lshlrev_b64 v[124:125], 11, v[174:175]
	v_or_b32_e32 v180, 16, v174
	v_lshl_add_u64 v[124:125], v[172:173], 0, v[124:125]
	v_ashrrev_i32_e32 v181, 31, v180
	global_load_dwordx4 v[190:193], v[124:125], off
	global_load_dwordx4 v[156:159], v[124:125], off offset:256
	v_lshlrev_b64 v[124:125], 11, v[180:181]
	v_or_b32_e32 v178, 32, v174
	v_lshl_add_u64 v[124:125], v[172:173], 0, v[124:125]
	v_ashrrev_i32_e32 v179, 31, v178
	global_load_dwordx4 v[152:155], v[124:125], off
	global_load_dwordx4 v[148:151], v[124:125], off offset:256
	v_lshlrev_b64 v[124:125], 11, v[178:179]
	v_or_b32_e32 v176, 48, v174
	v_lshl_add_u64 v[124:125], v[172:173], 0, v[124:125]
	v_ashrrev_i32_e32 v177, 31, v176
	global_load_dwordx4 v[144:147], v[124:125], off
	global_load_dwordx4 v[140:143], v[124:125], off offset:256
	v_lshlrev_b64 v[124:125], 11, v[176:177]
	v_lshl_add_u64 v[124:125], v[172:173], 0, v[124:125]
	global_load_dwordx4 v[136:139], v[124:125], off
	s_nop 0
	global_load_dwordx4 v[124:127], v[124:125], off offset:256
	v_add_u32_e32 v244, 0x80, v174
	v_ashrrev_i32_e32 v245, 31, v244
	v_lshlrev_b64 v[244:245], 11, v[244:245]
	v_lshl_add_u64 v[244:245], v[172:173], 0, v[244:245]
	global_load_dwordx4 v[202:205], v[244:245], off
	global_load_dwordx4 v[206:209], v[244:245], off offset:256
	v_add_u32_e32 v244, 0x90, v174
	v_ashrrev_i32_e32 v245, 31, v244
	v_lshlrev_b64 v[244:245], 11, v[244:245]
	v_lshl_add_u64 v[244:245], v[172:173], 0, v[244:245]
	global_load_dwordx4 v[210:213], v[244:245], off
	global_load_dwordx4 v[214:217], v[244:245], off offset:256
	v_add_u32_e32 v244, 0xa0, v174
	v_ashrrev_i32_e32 v245, 31, v244
	v_lshlrev_b64 v[244:245], 11, v[244:245]
	v_lshl_add_u64 v[244:245], v[172:173], 0, v[244:245]
	global_load_dwordx4 v[218:221], v[244:245], off
	global_load_dwordx4 v[222:225], v[244:245], off offset:256
	v_add_u32_e32 v244, 0xb0, v174
	v_ashrrev_i32_e32 v245, 31, v244
	v_lshlrev_b64 v[244:245], 11, v[244:245]
	v_lshl_add_u64 v[244:245], v[172:173], 0, v[244:245]
	global_load_dwordx4 v[226:229], v[244:245], off
	global_load_dwordx4 v[230:233], v[244:245], off offset:256
	v_cndmask_b32_e64 v182, 0, 1, s[52:53]
	v_cmp_ne_u32_e64 s[42:43], 1, v182
	v_lshlrev_b64 v[182:183], 10, v[174:175]
	v_lshl_add_u64 v[182:183], v[182:183], 0, v[170:171]
	s_mov_b64 s[18:19], -1
	s_andn2_b64 vcc, exec, s[52:53]
	s_waitcnt vmcnt(0)
	v_lshlrev_b32_e32 v184, 16, v190
	v_and_b32_e32 v185, 0xffff0000, v190
	v_lshlrev_b32_e32 v190, 16, v191
	v_and_b32_e32 v191, 0xffff0000, v191
	v_lshlrev_b32_e32 v194, 16, v192
	v_and_b32_e32 v195, 0xffff0000, v192
	v_lshlrev_b32_e32 v192, 16, v193
	v_and_b32_e32 v193, 0xffff0000, v193
	v_pk_add_f32 v[134:135], v[134:135], v[190:191]
	v_pk_add_f32 v[132:133], v[132:133], v[184:185]
	v_pk_add_f32 v[130:131], v[130:131], v[192:193]
	v_pk_add_f32 v[128:129], v[128:129], v[194:195]
	v_lshl_add_u64 v[184:185], v[182:183], 2, s[48:49]
	s_cbranch_vccnz .LBB0_177
	s_mov_b64 s[18:19], 0
	global_store_dwordx4 v[184:185], v[132:135], off
	global_store_dwordx4 v[184:185], v[128:131], off offset:16
